# G2 (Q-up/KV-up) GEMM epilogue: all rmsnorm-partial and rope loads of the 4 row groups of each half issued together with a single wait (was 12 serial load-wait rounds per half); sums keep original asso
# speedup vs baseline: 1.0152x; 1.0054x over previous
.LBB0_868:
	s_or_b32 vcc_lo, s13, s12
	s_cmp_eq_u32 vcc_lo, 1
	v_lshl_add_u32 v222, s44, 8, v232
	s_cselect_b64 s[44:45], -1, 0
	s_and_b64 s[8:9], s[44:45], exec
	s_cselect_b32 s8, s54, 0
	v_or_b32_e32 v0, s8, v235
	s_cselect_b32 s9, s68, s35
	s_cselect_b32 s8, s33, s34
	v_lshlrev_b32_e32 v0, 2, v0
	v_lshl_add_u64 v[218:219], s[8:9], 0, v[0:1]
	s_cselect_b32 s9, s70, s61
	s_cselect_b32 s8, s69, s60
	s_cmp_lg_u32 vcc_lo, 0
	v_lshl_add_u64 v[220:221], s[8:9], 0, v[0:1]
	s_cselect_b64 s[10:11], -1, 0
	s_cmp_eq_u32 vcc_lo, 0
	v_or_b32_e32 v223, 16, v222
	v_or_b32_e32 v227, 32, v222
	v_or_b32_e32 v229, 48, v222
	v_mov_b64_e32 v[60:61], s[48:49]
	s_nop 0
	v_mad_i64_i32 v[60:61], s[8:9], v222, s76, v[60:61]
	global_load_dwordx4 v[18:21], v[60:61], off
	global_load_dwordx4 v[22:25], v[60:61], off offset:16
	global_load_dwordx4 v[30:33], v[60:61], off offset:1280
	global_load_dwordx4 v[34:37], v[60:61], off offset:1296
	global_load_dwordx4 v[42:45], v[60:61], off offset:2560
	global_load_dwordx4 v[46:49], v[60:61], off offset:2576
	global_load_dwordx4 v[238:241], v[60:61], off offset:3840
	global_load_dwordx4 v[246:249], v[60:61], off offset:3856
	s_and_b64 vcc, exec, s[6:7]
	s_cbranch_vccnz .Lg2h1_nop2
	global_load_dwordx4 v[26:29], v[60:61], off offset:32
	global_load_dwordx4 v[38:41], v[60:61], off offset:1312
	global_load_dwordx4 v[50:53], v[60:61], off offset:2592
	global_load_dwordx4 v[54:57], v[60:61], off offset:3872
.Lg2h1_nop2:
	v_cndmask_b32_e64 v0, 0, 1, s[10:11]
	s_andn2_b64 vcc, exec, s[10:11]
	v_cmp_ne_u32_e64 s[8:9], 1, v0
	s_cbranch_vccnz .Lg2h1_norope
	s_and_b64 s[10:11], s[44:45], exec
	v_and_b32_e32 v0, 0x7cf, v222
	s_cselect_b32 s10, 5, 4
	v_lshlrev_b32_e32 v0, s10, v0
	v_lshlrev_b32_e32 v0, 2, v0
	s_lshl_b32 s100, 64, s10
	s_mov_b32 s101, 0
	v_lshl_add_u64 v[58:59], v[218:219], 0, v[0:1]
	v_lshl_add_u64 v[230:231], v[220:221], 0, v[0:1]
	global_load_dwordx4 v[2:5], v[58:59], off
	global_load_dwordx4 v[166:169], v[230:231], off
	v_lshl_add_u64 v[58:59], v[58:59], 0, s[100:101]
	v_lshl_add_u64 v[230:231], v[230:231], 0, s[100:101]
	global_load_dwordx4 v[6:9], v[58:59], off
	global_load_dwordx4 v[174:177], v[230:231], off
	v_lshl_add_u64 v[58:59], v[58:59], 0, s[100:101]
	v_lshl_add_u64 v[230:231], v[230:231], 0, s[100:101]
	global_load_dwordx4 v[10:13], v[58:59], off
	global_load_dwordx4 v[190:193], v[230:231], off
	v_lshl_add_u64 v[58:59], v[58:59], 0, s[100:101]
	v_lshl_add_u64 v[230:231], v[230:231], 0, s[100:101]
	global_load_dwordx4 v[14:17], v[58:59], off
	global_load_dwordx4 v[194:197], v[230:231], off
	s_branch .Lg2h1_wait
.Lg2h1_norope:
	v_mov_b32_e32 v2, 0
	v_mov_b32_e32 v3, 0
	v_mov_b32_e32 v4, 0
	v_mov_b32_e32 v5, 0
	v_mov_b32_e32 v6, s87
	v_mov_b32_e32 v7, s87
	v_mov_b32_e32 v8, s87
	v_mov_b32_e32 v9, s87
	v_mov_b32_e32 v10, s87
	v_mov_b32_e32 v11, s87
	v_mov_b32_e32 v12, s87
	v_mov_b32_e32 v13, s87
	v_mov_b32_e32 v14, s87
	v_mov_b32_e32 v15, s87
	v_mov_b32_e32 v16, s87
	v_mov_b32_e32 v17, s87
.Lg2h1_wait:
	s_waitcnt vmcnt(0)
	v_add_f32_e32 v18, v18, v19
	v_add_f32_e32 v20, v20, v21
	v_add_f32_e32 v22, v22, v23
	v_add_f32_e32 v24, v24, v25
	v_add_f32_e32 v18, v18, v20
	v_add_f32_e32 v22, v22, v24
	v_add_f32_e32 v226, v18, v22
	v_add_f32_e32 v30, v30, v31
	v_add_f32_e32 v32, v32, v33
	v_add_f32_e32 v34, v34, v35
	v_add_f32_e32 v36, v36, v37
	v_add_f32_e32 v30, v30, v32
	v_add_f32_e32 v34, v34, v36
	v_add_f32_e32 v228, v30, v34
	v_add_f32_e32 v42, v42, v43
	v_add_f32_e32 v44, v44, v45
	v_add_f32_e32 v46, v46, v47
	v_add_f32_e32 v48, v48, v49
	v_add_f32_e32 v42, v42, v44
	v_add_f32_e32 v46, v46, v48
	v_add_f32_e32 v230, v42, v46
	v_add_f32_e32 v238, v238, v239
	v_add_f32_e32 v240, v240, v241
	v_add_f32_e32 v246, v246, v247
	v_add_f32_e32 v248, v248, v249
	v_add_f32_e32 v238, v238, v240
	v_add_f32_e32 v246, v246, v248
	v_add_f32_e32 v58, v238, v246
	s_and_b64 vcc, exec, s[6:7]
	s_cbranch_vccnz .LBB0_888
	v_add_f32_e32 v26, v27, v26
	v_add_f32_e32 v28, v28, v29
	v_add_f32_e32 v26, v26, v28
	v_add_f32_e32 v226, v226, v26
	v_add_f32_e32 v38, v39, v38
	v_add_f32_e32 v40, v40, v41
	v_add_f32_e32 v38, v38, v40
	v_add_f32_e32 v228, v228, v38
	v_add_f32_e32 v50, v51, v50
	v_add_f32_e32 v52, v52, v53
	v_add_f32_e32 v50, v50, v52
	v_add_f32_e32 v230, v230, v50
	v_add_f32_e32 v54, v55, v54
	v_add_f32_e32 v56, v56, v57
	v_add_f32_e32 v54, v54, v56
	v_add_f32_e32 v58, v58, v54
.LBB0_888:
	v_div_scale_f32 v0, s[10:11], v236, v236, v226
	v_rcp_f32_e32 v59, v0
	s_cmp_eq_u32 s13, 0
	v_fma_f32 v60, -v0, v59, 1.0
	v_fmac_f32_e32 v59, v60, v59
	v_div_scale_f32 v60, vcc, v226, v236, v226
	v_mul_f32_e32 v61, v60, v59
	v_fma_f32 v224, -v0, v61, v60
	v_fmac_f32_e32 v61, v224, v59
	v_fma_f32 v0, -v0, v61, v60
	v_div_fmas_f32 v0, v0, v59, v61
	v_div_fixup_f32 v0, v0, v236, v226
	v_add_f32_e32 v0, 0x358637bd, v0
	v_cmp_gt_f32_e32 vcc, s75, v0
	v_mul_f32_e32 v59, 0x4b800000, v0
	s_nop 0
	v_cndmask_b32_e32 v0, v0, v59, vcc
	v_rsq_f32_e32 v0, v0
	s_nop 0
	v_mul_f32_e32 v59, 0x45800000, v0
	v_cndmask_b32_e32 v60, v0, v59, vcc
	v_div_scale_f32 v0, s[10:11], v236, v236, v230
	v_rcp_f32_e32 v59, v0
	s_nop 0
	v_fma_f32 v61, -v0, v59, 1.0
	v_fmac_f32_e32 v59, v61, v59
	v_div_scale_f32 v61, vcc, v230, v236, v230
	v_mul_f32_e32 v224, v61, v59
	v_fma_f32 v225, -v0, v224, v61
	v_fmac_f32_e32 v224, v225, v59
	v_fma_f32 v0, -v0, v224, v61
	v_div_fmas_f32 v0, v0, v59, v224
	v_div_fixup_f32 v0, v0, v236, v230
	v_add_f32_e32 v0, 0x358637bd, v0
	v_cmp_gt_f32_e32 vcc, s75, v0
	v_mul_f32_e32 v59, 0x4b800000, v0
	v_or_b32_e32 v230, s63, v233
	v_cndmask_b32_e32 v0, v0, v59, vcc
	v_rsq_f32_e32 v0, v0
	v_ashrrev_i32_e32 v231, 31, v230
	v_mul_f32_e32 v59, 0x45800000, v0
	v_cndmask_b32_e32 v0, v0, v59, vcc
	v_div_scale_f32 v59, s[10:11], v236, v236, v228
	v_rcp_f32_e32 v61, v59
	v_pk_mul_f32 v[150:151], v[150:151], v[0:1] op_sel_hi:[1,0]
	v_pk_mul_f32 v[152:153], v[152:153], v[0:1] op_sel_hi:[1,0]
	v_pk_mul_f32 v[142:143], v[142:143], v[0:1] op_sel_hi:[1,0]
	v_fma_f32 v224, -v59, v61, 1.0
	v_fmac_f32_e32 v61, v224, v61
	v_div_scale_f32 v224, vcc, v228, v236, v228
	v_mul_f32_e32 v225, v224, v61
	v_fma_f32 v226, -v59, v225, v224
	v_fmac_f32_e32 v225, v226, v61
	v_fma_f32 v59, -v59, v225, v224
	v_div_fmas_f32 v59, v59, v61, v225
	v_div_fixup_f32 v59, v59, v236, v228
	v_add_f32_e32 v59, 0x358637bd, v59
	v_cmp_gt_f32_e32 vcc, s75, v59
	v_mul_f32_e32 v61, 0x4b800000, v59
	v_pk_mul_f32 v[144:145], v[144:145], v[0:1] op_sel_hi:[1,0]
	v_cndmask_b32_e32 v59, v59, v61, vcc
	v_rsq_f32_e32 v59, v59
	v_pk_mul_f32 v[146:147], v[146:147], v[0:1] op_sel_hi:[1,0]
	v_pk_mul_f32 v[148:149], v[148:149], v[0:1] op_sel_hi:[1,0]
	v_mul_f32_e32 v61, 0x45800000, v59
	v_cndmask_b32_e32 v226, v59, v61, vcc
	v_div_scale_f32 v59, s[10:11], v236, v236, v58
	v_rcp_f32_e32 v61, v59
	s_cselect_b64 s[10:11], -1, 0
	s_cmp_eq_u32 s12, 0
	s_cselect_b64 s[12:13], -1, 0
	v_fma_f32 v224, -v59, v61, 1.0
	v_fmac_f32_e32 v61, v224, v61
	v_div_scale_f32 v224, vcc, v58, v236, v58
	v_mul_f32_e32 v225, v224, v61
	v_fma_f32 v228, -v59, v225, v224
	v_fmac_f32_e32 v225, v228, v61
	v_fma_f32 v59, -v59, v225, v224
	v_div_fmas_f32 v59, v59, v61, v225
	v_div_fixup_f32 v58, v59, v236, v58
	v_add_f32_e32 v58, 0x358637bd, v58
	v_cmp_gt_f32_e32 vcc, s75, v58
	v_mul_f32_e32 v59, 0x4b800000, v58
	v_pk_mul_f32 v[198:199], v[198:199], v[60:61] op_sel_hi:[1,0]
	v_cndmask_b32_e32 v58, v58, v59, vcc
	v_rsq_f32_e32 v58, v58
	v_pk_mul_f32 v[202:203], v[202:203], v[60:61] op_sel_hi:[1,0]
	v_pk_mul_f32 v[200:201], v[200:201], v[60:61] op_sel_hi:[1,0]
	v_pk_mul_f32 v[240:241], v[166:167], v[198:199]
	v_pk_mul_f32 v[246:247], v[198:199], v[2:3]
	v_pk_mul_f32 v[204:205], v[204:205], v[60:61] op_sel_hi:[1,0]
	v_pk_mul_f32 v[238:239], v[168:169], v[200:201]
	v_pk_fma_f32 v[240:241], v[202:203], v[2:3], v[240:241] neg_lo:[0,0,1] neg_hi:[0,0,1]
	v_pk_mul_f32 v[242:243], v[200:201], v[4:5]
	v_pk_fma_f32 v[246:247], v[166:167], v[202:203], v[246:247]
	v_mul_f32_e32 v59, 0x45800000, v58
	v_pk_fma_f32 v[238:239], v[204:205], v[4:5], v[238:239] neg_lo:[0,0,1] neg_hi:[0,0,1]
	v_pk_fma_f32 v[242:243], v[168:169], v[204:205], v[242:243]
	v_cndmask_b32_e64 v203, v241, v203, s[10:11]
	v_cndmask_b32_e64 v202, v240, v202, s[10:11]
	v_cndmask_b32_e64 v199, v247, v199, s[10:11]
	v_cndmask_b32_e64 v198, v246, v198, s[10:11]
	v_cndmask_b32_e32 v58, v58, v59, vcc
	v_cndmask_b32_e64 v59, v239, v205, s[10:11]
	v_cndmask_b32_e64 v61, v238, v204, s[10:11]
	v_cndmask_b32_e64 v204, v243, v201, s[10:11]
	v_cndmask_b32_e64 v205, v242, v200, s[10:11]
	v_cvt_pk_bf16_f32 v200, v202, v203
	v_cvt_pk_bf16_f32 v202, v198, v199
	v_mad_i64_i32 v[198:199], vcc, v222, s64, 0
	v_cvt_pk_bf16_f32 v203, v205, v204
	v_lshl_add_u64 v[204:205], v[198:199], 1, s[36:37]
	v_lshlrev_b64 v[198:199], 1, v[230:231]
	v_cvt_pk_bf16_f32 v201, v61, v59
	v_lshl_add_u64 v[204:205], v[204:205], 0, v[198:199]
	v_pk_mul_f32 v[186:187], v[186:187], v[60:61] op_sel_hi:[1,0]
	v_pk_mul_f32 v[188:189], v[188:189], v[60:61] op_sel_hi:[1,0]
	v_pk_mul_f32 v[182:183], v[182:183], v[60:61] op_sel_hi:[1,0]
	v_pk_mul_f32 v[60:61], v[184:185], v[60:61] op_sel_hi:[1,0]
	global_store_dwordx4 v[204:205], v[200:203], off
	v_pk_mul_f32 v[184:185], v[168:169], v[60:61]
	v_pk_mul_f32 v[230:231], v[182:183], v[2:3]
	v_pk_mul_f32 v[200:201], v[166:167], v[182:183]
	v_pk_mul_f32 v[202:203], v[60:61], v[4:5]
	v_pk_fma_f32 v[200:201], v[186:187], v[2:3], v[200:201] neg_lo:[0,0,1] neg_hi:[0,0,1]
	v_pk_fma_f32 v[184:185], v[188:189], v[4:5], v[184:185] neg_lo:[0,0,1] neg_hi:[0,0,1]
	v_pk_fma_f32 v[230:231], v[166:167], v[186:187], v[230:231]
	v_pk_fma_f32 v[202:203], v[168:169], v[188:189], v[202:203]
	v_cndmask_b32_e64 v59, v185, v189, s[12:13]
	v_cndmask_b32_e64 v184, v184, v188, s[12:13]
	v_cndmask_b32_e64 v185, v201, v187, s[12:13]
	v_cndmask_b32_e64 v186, v200, v186, s[12:13]
	v_cndmask_b32_e64 v61, v203, v61, s[12:13]
	v_cndmask_b32_e64 v60, v202, v60, s[12:13]
	v_cndmask_b32_e64 v187, v231, v183, s[12:13]
	v_cndmask_b32_e64 v188, v230, v182, s[12:13]
	v_cvt_pk_bf16_f32 v182, v186, v185
	v_cvt_pk_bf16_f32 v183, v184, v59
	v_cvt_pk_bf16_f32 v184, v188, v187
	v_cvt_pk_bf16_f32 v185, v60, v61
	v_pk_mul_f32 v[170:171], v[170:171], v[226:227] op_sel_hi:[1,0]
	global_store_dwordx4 v[204:205], v[182:185], off offset:256
	v_pk_mul_f32 v[60:61], v[178:179], v[226:227] op_sel_hi:[1,0]
	v_pk_mul_f32 v[172:173], v[172:173], v[226:227] op_sel_hi:[1,0]
	v_pk_mul_f32 v[182:183], v[174:175], v[170:171]
	v_pk_mul_f32 v[178:179], v[180:181], v[226:227] op_sel_hi:[1,0]
	v_pk_mul_f32 v[180:181], v[176:177], v[172:173]
	v_pk_fma_f32 v[182:183], v[60:61], v[6:7], v[182:183] neg_lo:[0,0,1] neg_hi:[0,0,1]
	v_pk_mul_f32 v[186:187], v[170:171], v[6:7]
	v_pk_fma_f32 v[180:181], v[178:179], v[8:9], v[180:181] neg_lo:[0,0,1] neg_hi:[0,0,1]
	v_pk_mul_f32 v[184:185], v[172:173], v[8:9]
	v_pk_fma_f32 v[186:187], v[174:175], v[60:61], v[186:187]
	v_cndmask_b32_e64 v61, v183, v61, s[10:11]
	v_cndmask_b32_e64 v60, v182, v60, s[10:11]
	v_pk_fma_f32 v[184:185], v[176:177], v[178:179], v[184:185]
	v_cndmask_b32_e64 v178, v180, v178, s[10:11]
	v_cndmask_b32_e64 v180, v186, v170, s[10:11]
	v_cvt_pk_bf16_f32 v170, v60, v61
	v_mad_i64_i32 v[60:61], vcc, v223, s64, 0
	v_cndmask_b32_e64 v59, v181, v179, s[10:11]
	v_cndmask_b32_e64 v173, v185, v173, s[10:11]
	v_cndmask_b32_e64 v179, v184, v172, s[10:11]
	v_cndmask_b32_e64 v172, v187, v171, s[10:11]
	v_lshl_add_u64 v[60:61], v[60:61], 1, s[36:37]
	v_cvt_pk_bf16_f32 v171, v178, v59
	v_cvt_pk_bf16_f32 v172, v180, v172
	v_cvt_pk_bf16_f32 v173, v179, v173
	v_lshl_add_u64 v[60:61], v[60:61], 0, v[198:199]
	v_pk_mul_f32 v[158:159], v[158:159], v[226:227] op_sel_hi:[1,0]
	v_pk_mul_f32 v[160:161], v[160:161], v[226:227] op_sel_hi:[1,0]
	global_store_dwordx4 v[60:61], v[170:173], off
	v_pk_mul_f32 v[162:163], v[162:163], v[226:227] op_sel_hi:[1,0]
	v_pk_mul_f32 v[164:165], v[164:165], v[226:227] op_sel_hi:[1,0]
	v_pk_mul_f32 v[170:171], v[176:177], v[160:161]
	v_pk_mul_f32 v[172:173], v[174:175], v[158:159]
	v_pk_mul_f32 v[178:179], v[160:161], v[8:9]
	v_pk_mul_f32 v[180:181], v[158:159], v[6:7]
	v_pk_fma_f32 v[172:173], v[162:163], v[6:7], v[172:173] neg_lo:[0,0,1] neg_hi:[0,0,1]
	v_pk_fma_f32 v[170:171], v[164:165], v[8:9], v[170:171] neg_lo:[0,0,1] neg_hi:[0,0,1]
	v_pk_fma_f32 v[180:181], v[174:175], v[162:163], v[180:181]
	v_pk_fma_f32 v[178:179], v[176:177], v[164:165], v[178:179]
	v_cndmask_b32_e64 v59, v171, v165, s[12:13]
	v_cndmask_b32_e64 v164, v170, v164, s[12:13]
	v_cndmask_b32_e64 v163, v173, v163, s[12:13]
	v_cndmask_b32_e64 v162, v172, v162, s[12:13]
	v_cndmask_b32_e64 v161, v179, v161, s[12:13]
	v_cndmask_b32_e64 v165, v178, v160, s[12:13]
	v_cndmask_b32_e64 v160, v181, v159, s[12:13]
	v_cndmask_b32_e64 v170, v180, v158, s[12:13]
	v_cvt_pk_bf16_f32 v158, v162, v163
	v_cvt_pk_bf16_f32 v159, v164, v59
	v_cvt_pk_bf16_f32 v160, v170, v160
	v_cvt_pk_bf16_f32 v161, v165, v161
	global_store_dwordx4 v[60:61], v[158:161], off offset:256
	v_pk_mul_f32 v[60:61], v[154:155], v[0:1] op_sel_hi:[1,0]
	v_pk_mul_f32 v[154:155], v[156:157], v[0:1] op_sel_hi:[1,0]
	v_pk_mul_f32 v[158:159], v[190:191], v[150:151]
	v_pk_mul_f32 v[156:157], v[192:193], v[152:153]
	v_pk_fma_f32 v[158:159], v[60:61], v[10:11], v[158:159] neg_lo:[0,0,1] neg_hi:[0,0,1]
	v_pk_mul_f32 v[162:163], v[150:151], v[10:11]
	v_pk_fma_f32 v[156:157], v[154:155], v[12:13], v[156:157] neg_lo:[0,0,1] neg_hi:[0,0,1]
	v_pk_mul_f32 v[160:161], v[152:153], v[12:13]
	v_pk_fma_f32 v[162:163], v[190:191], v[60:61], v[162:163]
	v_cndmask_b32_e64 v61, v159, v61, s[10:11]
	v_cndmask_b32_e64 v60, v158, v60, s[10:11]
	v_pk_fma_f32 v[160:161], v[192:193], v[154:155], v[160:161]
	v_cndmask_b32_e64 v154, v156, v154, s[10:11]
	v_cndmask_b32_e64 v156, v162, v150, s[10:11]
	v_cvt_pk_bf16_f32 v150, v60, v61
	v_mad_i64_i32 v[60:61], vcc, v227, s64, 0
	v_cndmask_b32_e64 v59, v157, v155, s[10:11]
	v_cndmask_b32_e64 v153, v161, v153, s[10:11]
	v_cndmask_b32_e64 v155, v160, v152, s[10:11]
	v_cndmask_b32_e64 v152, v163, v151, s[10:11]
	v_lshl_add_u64 v[60:61], v[60:61], 1, s[36:37]
	v_cvt_pk_bf16_f32 v151, v154, v59
	v_cvt_pk_bf16_f32 v152, v156, v152
	v_cvt_pk_bf16_f32 v153, v155, v153
	v_lshl_add_u64 v[60:61], v[60:61], 0, v[198:199]
	global_store_dwordx4 v[60:61], v[150:153], off
	v_pk_mul_f32 v[154:155], v[144:145], v[12:13]
	v_pk_mul_f32 v[156:157], v[142:143], v[10:11]
	v_pk_mul_f32 v[150:151], v[192:193], v[144:145]
	v_pk_mul_f32 v[152:153], v[190:191], v[142:143]
	v_pk_fma_f32 v[150:151], v[148:149], v[12:13], v[150:151] neg_lo:[0,0,1] neg_hi:[0,0,1]
	v_pk_fma_f32 v[152:153], v[146:147], v[10:11], v[152:153] neg_lo:[0,0,1] neg_hi:[0,0,1]
	v_pk_fma_f32 v[156:157], v[190:191], v[146:147], v[156:157]
	v_pk_fma_f32 v[154:155], v[192:193], v[148:149], v[154:155]
	v_cndmask_b32_e64 v0, v151, v149, s[12:13]
	v_cndmask_b32_e64 v59, v150, v148, s[12:13]
	v_cndmask_b32_e64 v147, v153, v147, s[12:13]
	v_cndmask_b32_e64 v146, v152, v146, s[12:13]
	v_cndmask_b32_e64 v145, v155, v145, s[12:13]
	v_cndmask_b32_e64 v148, v154, v144, s[12:13]
	v_cndmask_b32_e64 v144, v157, v143, s[12:13]
	v_cndmask_b32_e64 v149, v156, v142, s[12:13]
	v_cvt_pk_bf16_f32 v142, v146, v147
	v_cvt_pk_bf16_f32 v143, v59, v0
	v_cvt_pk_bf16_f32 v144, v149, v144
	v_cvt_pk_bf16_f32 v145, v148, v145
	v_pk_mul_f32 v[134:135], v[134:135], v[58:59] op_sel_hi:[1,0]
	global_store_dwordx4 v[60:61], v[142:145], off offset:256
	v_pk_mul_f32 v[60:61], v[138:139], v[58:59] op_sel_hi:[1,0]
	v_pk_mul_f32 v[136:137], v[136:137], v[58:59] op_sel_hi:[1,0]
	v_pk_mul_f32 v[142:143], v[194:195], v[134:135]
	v_pk_mul_f32 v[138:139], v[140:141], v[58:59] op_sel_hi:[1,0]
	v_pk_mul_f32 v[140:141], v[196:197], v[136:137]
	v_pk_fma_f32 v[142:143], v[14:15], v[60:61], v[142:143] neg_lo:[0,0,1] neg_hi:[0,0,1]
	v_pk_mul_f32 v[146:147], v[14:15], v[134:135]
	v_pk_fma_f32 v[140:141], v[16:17], v[138:139], v[140:141] neg_lo:[0,0,1] neg_hi:[0,0,1]
	v_pk_mul_f32 v[144:145], v[16:17], v[136:137]
	v_pk_fma_f32 v[146:147], v[194:195], v[60:61], v[146:147]
	v_cndmask_b32_e64 v61, v143, v61, s[10:11]
	v_cndmask_b32_e64 v60, v142, v60, s[10:11]
	v_pk_fma_f32 v[144:145], v[196:197], v[138:139], v[144:145]
	v_cndmask_b32_e64 v0, v141, v139, s[10:11]
	v_cndmask_b32_e64 v139, v146, v134, s[10:11]
	v_cvt_pk_bf16_f32 v134, v60, v61
	v_mad_i64_i32 v[60:61], vcc, v229, s64, 0
	v_cndmask_b32_e64 v59, v140, v138, s[10:11]
	v_cndmask_b32_e64 v137, v145, v137, s[10:11]
	v_cndmask_b32_e64 v138, v144, v136, s[10:11]
	v_cndmask_b32_e64 v136, v147, v135, s[10:11]
	v_lshl_add_u64 v[60:61], v[60:61], 1, s[36:37]
	v_cvt_pk_bf16_f32 v135, v59, v0
	v_cvt_pk_bf16_f32 v136, v139, v136
	v_cvt_pk_bf16_f32 v137, v138, v137
	v_lshl_add_u64 v[138:139], v[60:61], 0, v[198:199]
	v_pk_mul_f32 v[60:61], v[130:131], v[58:59] op_sel_hi:[1,0]
	v_pk_mul_f32 v[130:131], v[132:133], v[58:59] op_sel_hi:[1,0]
	v_pk_mul_f32 v[126:127], v[126:127], v[58:59] op_sel_hi:[1,0]
	v_pk_mul_f32 v[58:59], v[128:129], v[58:59] op_sel_hi:[1,0]
	global_store_dwordx4 v[138:139], v[134:137], off
	v_pk_mul_f32 v[128:129], v[196:197], v[58:59]
	v_pk_mul_f32 v[132:133], v[194:195], v[126:127]
	v_pk_mul_f32 v[134:135], v[16:17], v[58:59]
	v_pk_mul_f32 v[136:137], v[14:15], v[126:127]
	v_pk_fma_f32 v[132:133], v[14:15], v[60:61], v[132:133] neg_lo:[0,0,1] neg_hi:[0,0,1]
	v_pk_fma_f32 v[128:129], v[16:17], v[130:131], v[128:129] neg_lo:[0,0,1] neg_hi:[0,0,1]
	v_pk_fma_f32 v[136:137], v[194:195], v[60:61], v[136:137]
	v_pk_fma_f32 v[134:135], v[196:197], v[130:131], v[134:135]
	v_cndmask_b32_e64 v0, v129, v131, s[12:13]
	v_cndmask_b32_e64 v128, v128, v130, s[12:13]
	v_cndmask_b32_e64 v61, v133, v61, s[12:13]
	v_cndmask_b32_e64 v60, v132, v60, s[12:13]
	v_cndmask_b32_e64 v129, v135, v59, s[12:13]
	v_cndmask_b32_e64 v130, v134, v58, s[12:13]
	v_cndmask_b32_e64 v127, v137, v127, s[12:13]
	v_cndmask_b32_e64 v126, v136, v126, s[12:13]
	v_cvt_pk_bf16_f32 v58, v60, v61
	v_cvt_pk_bf16_f32 v59, v128, v0
	v_cvt_pk_bf16_f32 v60, v126, v127
	v_cvt_pk_bf16_f32 v61, v130, v129
	v_add_u32_e32 v126, 0x80, v222
	s_and_b64 vcc, exec, s[8:9]
	global_store_dwordx4 v[138:139], v[58:61], off offset:256
	v_add_u32_e32 v37, 0x90, v222
	v_add_u32_e32 v35, 0xa0, v222
	v_add_u32_e32 v21, 0xb0, v222
	v_mov_b64_e32 v[38:39], s[48:49]
	s_nop 0
	v_mad_i64_i32 v[38:39], vcc, v126, s76, v[38:39]
	global_load_dwordx4 v[128:131], v[38:39], off
	global_load_dwordx4 v[132:135], v[38:39], off offset:16
	global_load_dwordx4 v[140:143], v[38:39], off offset:1280
	global_load_dwordx4 v[144:147], v[38:39], off offset:1296
	global_load_dwordx4 v[152:155], v[38:39], off offset:2560
	global_load_dwordx4 v[156:159], v[38:39], off offset:2576
	global_load_dwordx4 v[178:181], v[38:39], off offset:3840
	global_load_dwordx4 v[182:185], v[38:39], off offset:3856
	s_and_b64 vcc, exec, s[6:7]
	s_cbranch_vccnz .Lg2h2_nop2
	global_load_dwordx4 v[136:139], v[38:39], off offset:32
	global_load_dwordx4 v[148:151], v[38:39], off offset:1312
	global_load_dwordx4 v[160:163], v[38:39], off offset:2592
	global_load_dwordx4 v[186:189], v[38:39], off offset:3872
.Lg2h2_nop2:
	s_and_b64 vcc, exec, s[8:9]
	s_cbranch_vccnz .Lg2h2_wait
	s_and_b64 vcc, s[44:45], exec
	v_and_b32_e32 v0, 0x7cf, v126
	s_cselect_b32 s63, 5, 4
	v_lshlrev_b32_e32 v0, s63, v0
	v_lshlrev_b32_e32 v0, 2, v0
	s_lshl_b32 s100, 64, s63
	s_mov_b32 s101, 0
	v_lshl_add_u64 v[40:41], v[218:219], 0, v[0:1]
	v_lshl_add_u64 v[42:43], v[220:221], 0, v[0:1]
	global_load_dwordx4 v[2:5], v[40:41], off
	global_load_dwordx4 v[166:169], v[42:43], off
	v_lshl_add_u64 v[40:41], v[40:41], 0, s[100:101]
	v_lshl_add_u64 v[42:43], v[42:43], 0, s[100:101]
	global_load_dwordx4 v[6:9], v[40:41], off
	global_load_dwordx4 v[174:177], v[42:43], off
	v_lshl_add_u64 v[40:41], v[40:41], 0, s[100:101]
	v_lshl_add_u64 v[42:43], v[42:43], 0, s[100:101]
	global_load_dwordx4 v[10:13], v[40:41], off
	global_load_dwordx4 v[190:193], v[42:43], off
	v_lshl_add_u64 v[40:41], v[40:41], 0, s[100:101]
	v_lshl_add_u64 v[42:43], v[42:43], 0, s[100:101]
	global_load_dwordx4 v[14:17], v[40:41], off
	global_load_dwordx4 v[194:197], v[42:43], off
.Lg2h2_wait:
	s_waitcnt vmcnt(0)
	v_add_f32_e32 v128, v128, v129
	v_add_f32_e32 v130, v130, v131
	v_add_f32_e32 v132, v132, v133
	v_add_f32_e32 v134, v134, v135
	v_add_f32_e32 v128, v128, v130
	v_add_f32_e32 v132, v132, v134
	v_add_f32_e32 v36, v128, v132
	v_add_f32_e32 v140, v140, v141
	v_add_f32_e32 v142, v142, v143
	v_add_f32_e32 v144, v144, v145
	v_add_f32_e32 v146, v146, v147
	v_add_f32_e32 v140, v140, v142
	v_add_f32_e32 v144, v144, v146
	v_add_f32_e32 v34, v140, v144
	v_add_f32_e32 v152, v152, v153
	v_add_f32_e32 v154, v154, v155
	v_add_f32_e32 v156, v156, v157
	v_add_f32_e32 v158, v158, v159
	v_add_f32_e32 v152, v152, v154
	v_add_f32_e32 v156, v156, v158
	v_add_f32_e32 v20, v152, v156
	v_add_f32_e32 v178, v178, v179
	v_add_f32_e32 v180, v180, v181
	v_add_f32_e32 v182, v182, v183
	v_add_f32_e32 v184, v184, v185
	v_add_f32_e32 v178, v178, v180
	v_add_f32_e32 v182, v182, v184
	v_add_f32_e32 v18, v178, v182
	s_and_b64 vcc, exec, s[6:7]
	s_cbranch_vccnz .LBB0_853
	v_add_f32_e32 v136, v137, v136
	v_add_f32_e32 v138, v138, v139
	v_add_f32_e32 v136, v136, v138
	v_add_f32_e32 v36, v36, v136
	v_add_f32_e32 v148, v149, v148
	v_add_f32_e32 v150, v150, v151
	v_add_f32_e32 v148, v148, v150
	v_add_f32_e32 v34, v34, v148
	v_add_f32_e32 v160, v161, v160
	v_add_f32_e32 v162, v162, v163
	v_add_f32_e32 v160, v160, v162
	v_add_f32_e32 v20, v20, v160
	v_add_f32_e32 v186, v187, v186
	v_add_f32_e32 v188, v188, v189
	v_add_f32_e32 v186, v186, v188
	v_add_f32_e32 v18, v18, v186
	s_branch .LBB0_853
